# v27 plus QK-norm+rope row loop fast path: 3 head slots reduced together, next-row loads issued before stores
# baseline (speedup 1.0000x reference)
; DI int otid() { int t = threadIdx.x; asm volatile("" : "+v"(t)); return t; }
; DI int obid() { int b = blockIdx.x; asm volatile("" : "+s"(b)); return b; }
; #define ROW_LOOP(row, NROWS, BID, NB, WID) \
;   for (int it_ = 0, row = ((NB) == 256 ? ((((BID) & 7)) << 8) + (((BID) >> 3) << 3) + (WID) : (BID) * 8 + (WID)); row < (NROWS); \
;        ++it_, row = ((NB) == 256 ? ((((BID) & 7) + 8 * it_) << 8) + (((BID) >> 3) << 3) + (WID) : (BID) * 8 + (WID) + it_ * (NB) * 8))
; DI KParams kp() { KParams k = (KParams)__builtin_amdgcn_kernarg_segment_ptr(); asm volatile("" : "+s"(k)); return k; }
; DI void phase_att_normrope() {
;   KParams P = kp(); char* ws = P->ws;
;   const int nb = gridDim.x, bid = obid(), lane = otid() & 63, wid = otid() >> 6;
;   u16* QKV = GBP(u16, A_QKV); const float2* taba = WSP(float2, OFF_TABA);
;   const float* qg = P->att_q_gain; const float* kg = P->att_k_gain;
;   const int l16 = lane & 15, blk = l16 >> 3, j = (l16 & 7) * 4, da = blk * 64 + j;
;   const f32x4 gqa = *(const f32x4*)(qg + da), gqb = *(const f32x4*)(qg + da + 32), gka = *(const f32x4*)(kg + da), gkb = *(const f32x4*)(kg + da + 32);
;   ROW_LOOP(t, TA, bid, nb, wid) {
.LBB0_1078:
	s_mov_b64 s[8:9], s[96:97]
	s_waitcnt vmcnt(63) expcnt(7) lgkmcnt(15)
	s_mov_b32 s17, s80
	v_mov_b32_e32 v18, v182
	s_load_dwordx4 s[20:23], s[8:9], 0x60
	s_load_dwordx2 s[10:11], s[8:9], 0x98
	v_mov_b32_e32 v20, v182
	v_lshlrev_b32_e32 v0, 2, v18
	v_bfe_u32 v16, v18, 3, 1
	v_and_b32_e32 v17, 28, v0
	v_lshl_or_b32 v19, v16, 6, v17
	v_lshlrev_b32_e32 v4, 2, v19
	s_waitcnt lgkmcnt(0)
	global_load_dwordx4 v[8:11], v4, s[20:21]
	global_load_dwordx4 v[68:71], v4, s[20:21]
	global_load_dwordx4 v[72:75], v4, s[20:21] offset:128
	global_load_dwordx4 v[76:79], v4, s[22:23]
	global_load_dwordx4 v[80:83], v4, s[22:23] offset:128
	global_load_dwordx4 v[12:15], v4, s[22:23]
	global_load_dwordx4 v[0:3], v4, s[20:21] offset:128
	s_nop 0
	global_load_dwordx4 v[4:7], v4, s[22:23] offset:128
	s_mov_b64 s[8:9], -1
	s_and_b64 vcc, exec, s[86:87]
	s_cbranch_vccz .LBB0_1080
	s_lshl_b32 s12, s17, 3
	s_mov_b64 s[8:9], 0

; #define ROW_LOOP(row, NROWS, BID, NB, WID) \
;   for (int it_ = 0, row = ((NB) == 256 ? ((((BID) & 7)) << 8) + (((BID) >> 3) << 3) + (WID) : (BID) * 8 + (WID)); row < (NROWS); \
;        ++it_, row = ((NB) == 256 ? ((((BID) & 7) + 8 * it_) << 8) + (((BID) >> 3) << 3) + (WID) : (BID) * 8 + (WID) + it_ * (NB) * 8))
; DI void phase_att_normrope() {
;     ...
;   ROW_LOOP(t, TA, bid, nb, wid) {
;     const int pos = t & 4095, idx = blk ? (pos & 63) : (pos >> 6);
;     u16* row = QKV + (size_t)t * 1536;
;     const f32x4 cs01 = *(const f32x4*)(taba + idx * 32 + j), cs23 = *(const f32x4*)(taba + idx * 32 + j + 2);
;     u32x2 ra[3], rb[3];
; #pragma unroll
;     for (int s = 0; s < 3; ++s) {
;       const int hs = s * 4 + (lane >> 4);
;       if (hs < 10) { ra[s] = *(const u32x2*)(row + hs * 128 + da); rb[s] = *(const u32x2*)(row + hs * 128 + da + 32); }
;       else { ra[s] = u32x2{0u, 0u}; rb[s] = u32x2{0u, 0u}; }
;     }
; #pragma unroll
;     for (int s = 0; s < 3; ++s) {
;       const int hs = s * 4 + (lane >> 4);
;       float a[4] = {__uint_as_float(ra[s][0] << 16), __uint_as_float(ra[s][0] & 0xffff0000u), __uint_as_float(ra[s][1] << 16), __uint_as_float(ra[s][1] & 0xffff0000u)};
;       float b[4] = {__uint_as_float(rb[s][0] << 16), __uint_as_float(rb[s][0] & 0xffff0000u), __uint_as_float(rb[s][1] << 16), __uint_as_float(rb[s][1] & 0xffff0000u)};
;       float ss = a[0] * a[0] + a[1] * a[1] + a[2] * a[2] + a[3] * a[3] + b[0] * b[0] + b[1] * b[1] + b[2] * b[2] + b[3] * b[3];
; #pragma unroll
;       for (int o = 8; o; o >>= 1) ss += __shfl_xor(ss, o);
;       const float rstd = rsqrtf(ss * (1.f / 128.f) + EPS);
.LBB0_1082:
	v_ashrrev_i32_e32 v21, 6, v20
	v_add_u32_e32 v31, s12, v21
	v_cmp_gt_i32_e32 vcc, s81, v31
	s_and_saveexec_b64 s[18:19], vcc
	s_cbranch_execz .LBB0_1091
	v_bfe_u32 v20, v18, 4, 2
	v_and_b32_e32 v18, 64, v183
	v_add_u32_e32 v22, 64, v18
	v_xor_b32_e32 v23, 8, v183
	v_cmp_lt_i32_e32 vcc, v23, v22
	v_lshlrev_b32_e32 v176, 3, v17
	v_cmp_eq_u32_e64 s[8:9], 0, v16
	v_cndmask_b32_e32 v23, v183, v23, vcc
	v_lshlrev_b32_e32 v48, 2, v23
	v_xor_b32_e32 v23, 4, v183
	v_cmp_lt_i32_e32 vcc, v23, v22
	v_lshl_add_u64 v[16:17], s[10:11], 0, v[176:177]
	s_mov_b64 s[12:13], 0x3628000
	v_cndmask_b32_e32 v23, v183, v23, vcc
	v_lshlrev_b32_e32 v49, 2, v23
	v_xor_b32_e32 v23, 2, v183
	v_cmp_lt_i32_e32 vcc, v23, v22
	v_lshl_add_u64 v[16:17], v[16:17], 0, s[12:13]
	s_lshl_b32 s12, s17, 8
	v_cndmask_b32_e32 v23, v183, v23, vcc
	v_lshlrev_b32_e32 v50, 2, v23
	v_xor_b32_e32 v23, 1, v183
	s_and_b32 s20, s12, 0x700
	s_and_b32 s21, s17, -8
	v_lshlrev_b32_e32 v176, 1, v19
	v_cmp_lt_i32_e32 vcc, v23, v22
	v_lshl_add_u64 v[18:19], s[10:11], 0, v[176:177]
	s_mov_b64 s[10:11], 0x762c100
	v_lshlrev_b32_e32 v30, 7, v20
	v_or_b32_e32 v20, 8, v20
	v_cndmask_b32_e32 v22, v183, v23, vcc
	s_add_i32 s20, s20, s21
	s_mov_b32 s24, 0
	v_lshl_add_u64 v[18:19], v[18:19], 0, s[10:11]
	v_cmp_gt_u32_e64 s[10:11], 10, v20
	v_cmp_lt_u32_e64 s[12:13], 9, v20
	v_lshlrev_b32_e32 v20, 7, v20
	v_lshlrev_b32_e32 v51, 2, v22
	s_waitcnt vmcnt(0)
	v_mov_b32_e32 v22, v14
	v_mov_b32_e32 v23, v6
	v_mov_b32_e32 v6, v15
	v_mov_b32_e32 v24, v12
	v_mov_b32_e32 v25, v4
	v_mov_b32_e32 v4, v13
	v_mov_b32_e32 v26, v10
	v_mov_b32_e32 v27, v2
	v_mov_b32_e32 v2, v11
	v_mov_b32_e32 v28, v8
	v_mov_b32_e32 v29, v0
	v_mov_b32_e32 v0, v9
	s_add_i32 s25, s20, 0x800
	s_mov_b64 s[20:21], 0
	v_lshlrev_b32_e32 v30, 1, v30
	s_and_b64 vcc, exec, s[4:5]
	s_cbranch_vccz .LBB0_1085
	v_readfirstlane_b32 s25, v31
	v_mov_b32_e32 v61, 0
	v_mov_b32_e32 v124, v30
	v_mov_b32_e32 v125, 0
	v_lshl_add_u64 v[124:125], v[124:125], 0, v[18:19]
	v_lshlrev_b32_e32 v126, 1, v20
	v_mov_b32_e32 v127, 0
	v_lshl_add_u64 v[126:127], v[126:127], 0, v[18:19]
	s_mov_b32 s20, s25
	s_lshr_b32 s22, s20, 6
	s_and_b32 s22, s22, 63
	s_lshl_b32 s22, s22, 8
	s_and_b32 s21, s20, 63
	s_lshl_b32 s21, s21, 8
	v_mov_b32_e32 v61, s21
	v_mov_b32_e32 v176, s22
	v_cndmask_b32_e64 v66, v61, v176, s[8:9]
	v_mov_b32_e32 v67, 0
	v_lshl_add_u64 v[66:67], v[66:67], 0, v[16:17]
	s_mul_i32 s22, s20, 0xc00
	s_mov_b32 s23, 0
	v_lshl_add_u64 v[62:63], v[124:125], 0, s[22:23]
	v_lshl_add_u64 v[64:65], v[126:127], 0, s[22:23]
	global_load_dwordx4 v[104:107], v[66:67], off
	global_load_dwordx4 v[108:111], v[66:67], off offset:16
	global_load_dwordx2 v[112:113], v[62:63], off
	global_load_dwordx2 v[114:115], v[62:63], off offset:64
	global_load_dwordx2 v[116:117], v[62:63], off offset:1024
	global_load_dwordx2 v[118:119], v[62:63], off offset:1088
	global_load_dwordx2 v[120:121], v[64:65], off
	global_load_dwordx2 v[122:123], v[64:65], off offset:64
	s_waitcnt vmcnt(0)
	s_branch .Lfr_body
.Lfr_top:
	s_waitcnt vmcnt(6)
.Lfr_body:
	v_mov_b32_e32 v84, v104
	v_mov_b32_e32 v85, v105
	v_mov_b32_e32 v86, v106
	v_mov_b32_e32 v87, v107
	v_mov_b32_e32 v88, v108
	v_mov_b32_e32 v89, v109
	v_mov_b32_e32 v90, v110
	v_mov_b32_e32 v91, v111
	v_mov_b32_e32 v92, v112
	v_mov_b32_e32 v93, v113
	v_mov_b32_e32 v94, v114
	v_mov_b32_e32 v95, v115
	v_mov_b32_e32 v96, v116
	v_mov_b32_e32 v97, v117
	v_mov_b32_e32 v98, v118
	v_mov_b32_e32 v99, v119
	v_mov_b32_e32 v100, v120
	v_mov_b32_e32 v101, v121
	v_mov_b32_e32 v102, v122
	v_mov_b32_e32 v103, v123
	s_add_i32 s24, s25, 0x800
	s_cmp_lt_i32 s24, 0x8000
	s_cselect_b32 s20, s24, s25
	s_lshr_b32 s22, s20, 6
	s_and_b32 s22, s22, 63
	s_lshl_b32 s22, s22, 8
	s_and_b32 s21, s20, 63
	s_lshl_b32 s21, s21, 8
	v_mov_b32_e32 v61, s21
	v_mov_b32_e32 v176, s22
	v_cndmask_b32_e64 v66, v61, v176, s[8:9]
	v_mov_b32_e32 v67, 0
	v_lshl_add_u64 v[66:67], v[66:67], 0, v[16:17]
	s_mul_i32 s22, s20, 0xc00
	s_mov_b32 s23, 0
	v_lshl_add_u64 v[62:63], v[124:125], 0, s[22:23]
	v_lshl_add_u64 v[64:65], v[126:127], 0, s[22:23]
	global_load_dwordx4 v[104:107], v[66:67], off
	global_load_dwordx4 v[108:111], v[66:67], off offset:16
	global_load_dwordx2 v[112:113], v[62:63], off
	global_load_dwordx2 v[114:115], v[62:63], off offset:64
	global_load_dwordx2 v[116:117], v[62:63], off offset:1024
	global_load_dwordx2 v[118:119], v[62:63], off offset:1088
	global_load_dwordx2 v[120:121], v[64:65], off
	global_load_dwordx2 v[122:123], v[64:65], off offset:64
	s_mul_i32 s22, s25, 0xc00
	v_lshl_add_u64 v[62:63], v[124:125], 0, s[22:23]
	v_lshl_add_u64 v[64:65], v[126:127], 0, s[22:23]
	v_lshlrev_b32_e32 v8, 16, v92
	v_and_b32_e32 v9, 0xffff0000, v92
	v_lshlrev_b32_e32 v10, 16, v93
	v_and_b32_e32 v11, 0xffff0000, v93
	v_lshlrev_b32_e32 v12, 16, v94
	v_and_b32_e32 v13, 0xffff0000, v94
	v_lshlrev_b32_e32 v14, 16, v95
	v_and_b32_e32 v15, 0xffff0000, v95
	v_lshlrev_b32_e32 v32, 16, v96
	v_and_b32_e32 v33, 0xffff0000, v96
	v_lshlrev_b32_e32 v34, 16, v97
	v_and_b32_e32 v35, 0xffff0000, v97
	v_lshlrev_b32_e32 v36, 16, v98
	v_and_b32_e32 v37, 0xffff0000, v98
	v_lshlrev_b32_e32 v38, 16, v99
	v_and_b32_e32 v39, 0xffff0000, v99
	v_lshlrev_b32_e32 v40, 16, v100
	v_and_b32_e32 v41, 0xffff0000, v100
	v_lshlrev_b32_e32 v42, 16, v101
	v_and_b32_e32 v43, 0xffff0000, v101
	v_lshlrev_b32_e32 v44, 16, v102
	v_and_b32_e32 v45, 0xffff0000, v102
	v_lshlrev_b32_e32 v46, 16, v103
	v_and_b32_e32 v47, 0xffff0000, v103
	v_mul_f32_e32 v52, v8, v8
	v_mul_f32_e32 v53, v32, v32
	v_mul_f32_e32 v54, v40, v40
	v_fmac_f32_e32 v52, v9, v9
	v_fmac_f32_e32 v53, v33, v33
	v_fmac_f32_e32 v54, v41, v41
	v_fmac_f32_e32 v52, v10, v10
	v_fmac_f32_e32 v53, v34, v34
	v_fmac_f32_e32 v54, v42, v42
	v_fmac_f32_e32 v52, v11, v11
	v_fmac_f32_e32 v53, v35, v35
	v_fmac_f32_e32 v54, v43, v43
	v_fmac_f32_e32 v52, v12, v12
	v_fmac_f32_e32 v53, v36, v36
	v_fmac_f32_e32 v54, v44, v44
	v_fmac_f32_e32 v52, v13, v13
	v_fmac_f32_e32 v53, v37, v37
	v_fmac_f32_e32 v54, v45, v45
	v_fmac_f32_e32 v52, v14, v14
	v_fmac_f32_e32 v53, v38, v38
	v_fmac_f32_e32 v54, v46, v46
	v_fmac_f32_e32 v52, v15, v15
	v_fmac_f32_e32 v53, v39, v39
	v_fmac_f32_e32 v54, v47, v47
	ds_bpermute_b32 v55, v48, v52
	ds_bpermute_b32 v56, v48, v53
	ds_bpermute_b32 v57, v48, v54
	s_waitcnt lgkmcnt(0)
; DI void st4(u16* p, float a, float b, float c, float d) { u32x2 w = {cvtpk(a, b), cvtpk(c, d)}; *(u32x2*)p = w; }
; DI void phase_att_normrope() {
;     ...
;     for (int s = 0; s < 3; ++s) {
;       const int hs = s * 4 + (lane >> 4);
;       float a[4] = {__uint_as_float(ra[s][0] << 16), __uint_as_float(ra[s][0] & 0xffff0000u), __uint_as_float(ra[s][1] << 16), __uint_as_float(ra[s][1] & 0xffff0000u)};
;       float b[4] = {__uint_as_float(rb[s][0] << 16), __uint_as_float(rb[s][0] & 0xffff0000u), __uint_as_float(rb[s][1] << 16), __uint_as_float(rb[s][1] & 0xffff0000u)};
;       float ss = a[0] * a[0] + a[1] * a[1] + a[2] * a[2] + a[3] * a[3] + b[0] * b[0] + b[1] * b[1] + b[2] * b[2] + b[3] * b[3];
; #pragma unroll
;       for (int o = 8; o; o >>= 1) ss += __shfl_xor(ss, o);
;       const float rstd = rsqrtf(ss * (1.f / 128.f) + EPS);
;       const f32x4 ga = (hs < 8) ? gqa : gka, gb = (hs < 8) ? gqb : gkb;
;       const float cs[8] = {cs01[0], cs01[1], cs01[2], cs01[3], cs23[0], cs23[1], cs23[2], cs23[3]};
;       float oa[4], ob[4];
; #pragma unroll
;       for (int q = 0; q < 4; ++q) {
;         const float x = a[q] * rstd * ga[q], y = b[q] * rstd * gb[q];
;         oa[q] = x * cs[2 * q] - y * cs[2 * q + 1];
;         ob[q] = x * cs[2 * q + 1] + y * cs[2 * q];
;       }
;       if (hs < 10) { st4(row + hs * 128 + da, oa[0], oa[1], oa[2], oa[3]); st4(row + hs * 128 + da + 32, ob[0], ob[1], ob[2], ob[3]); }
;     }
	v_add_f32_e32 v52, v52, v55
	v_add_f32_e32 v53, v53, v56
	v_add_f32_e32 v54, v54, v57
	ds_bpermute_b32 v55, v49, v52
	ds_bpermute_b32 v56, v49, v53
	ds_bpermute_b32 v57, v49, v54
	s_waitcnt lgkmcnt(0)
	v_add_f32_e32 v52, v52, v55
	v_add_f32_e32 v53, v53, v56
	v_add_f32_e32 v54, v54, v57
	ds_bpermute_b32 v55, v50, v52
	ds_bpermute_b32 v56, v50, v53
	ds_bpermute_b32 v57, v50, v54
	s_waitcnt lgkmcnt(0)
	v_add_f32_e32 v52, v52, v55
	v_add_f32_e32 v53, v53, v56
	v_add_f32_e32 v54, v54, v57
	ds_bpermute_b32 v55, v51, v52
	ds_bpermute_b32 v56, v51, v53
	ds_bpermute_b32 v57, v51, v54
	s_waitcnt lgkmcnt(0)
	v_add_f32_e32 v52, v52, v55
	v_add_f32_e32 v53, v53, v56
	v_add_f32_e32 v54, v54, v57
	v_fmamk_f32 v61, v52, 0x3c000000, v188
	v_cmp_gt_f32_e32 vcc, 0x800000, v61
	v_mul_f32_e32 v176, 0x4b800000, v61
	s_nop 1
	v_cndmask_b32_e32 v61, v61, v176, vcc
	v_rsq_f32_e32 v61, v61
	s_nop 0
	v_mul_f32_e32 v176, 0x45800000, v61
	v_cndmask_b32_e32 v58, v61, v176, vcc
	v_fmamk_f32 v61, v53, 0x3c000000, v188
	v_cmp_gt_f32_e32 vcc, 0x800000, v61
	v_mul_f32_e32 v176, 0x4b800000, v61
	s_nop 1
	v_cndmask_b32_e32 v61, v61, v176, vcc
	v_rsq_f32_e32 v61, v61
	s_nop 0
	v_mul_f32_e32 v176, 0x45800000, v61
	v_cndmask_b32_e32 v59, v61, v176, vcc
	v_fmamk_f32 v61, v54, 0x3c000000, v188
	v_cmp_gt_f32_e32 vcc, 0x800000, v61
	v_mul_f32_e32 v176, 0x4b800000, v61
	s_nop 1
	v_cndmask_b32_e32 v61, v61, v176, vcc
	v_rsq_f32_e32 v61, v61
	s_nop 0
	v_mul_f32_e32 v176, 0x45800000, v61
	v_cndmask_b32_e32 v60, v61, v176, vcc
	v_mul_f32_e32 v8, v8, v58
	v_mul_f32_e32 v12, v12, v58
	v_mul_f32_e32 v8, v8, v68
	v_mul_f32_e32 v12, v12, v72
	v_mul_f32_e32 v61, v12, v85
	v_mul_f32_e32 v176, v12, v84
	v_fma_f32 v61, v8, v84, -v61
	v_fma_f32 v176, v8, v85, v176
	v_mov_b32_e32 v8, v61
	v_mov_b32_e32 v12, v176
	v_mul_f32_e32 v9, v9, v58
	v_mul_f32_e32 v13, v13, v58
	v_mul_f32_e32 v9, v9, v69
	v_mul_f32_e32 v13, v13, v73
	v_mul_f32_e32 v61, v13, v87
	v_mul_f32_e32 v176, v13, v86
	v_fma_f32 v61, v9, v86, -v61
	v_fma_f32 v176, v9, v87, v176
	v_mov_b32_e32 v9, v61
	v_mov_b32_e32 v13, v176
	v_mul_f32_e32 v10, v10, v58
	v_mul_f32_e32 v14, v14, v58
	v_mul_f32_e32 v10, v10, v70
	v_mul_f32_e32 v14, v14, v74
	v_mul_f32_e32 v61, v14, v89
	v_mul_f32_e32 v176, v14, v88
	v_fma_f32 v61, v10, v88, -v61
	v_fma_f32 v176, v10, v89, v176
	v_mov_b32_e32 v10, v61
	v_mov_b32_e32 v14, v176
	v_mul_f32_e32 v11, v11, v58
	v_mul_f32_e32 v15, v15, v58
	v_mul_f32_e32 v11, v11, v71
	v_mul_f32_e32 v15, v15, v75
	v_mul_f32_e32 v61, v15, v91
	v_mul_f32_e32 v176, v15, v90
	v_fma_f32 v61, v11, v90, -v61
	v_fma_f32 v176, v11, v91, v176
	v_mov_b32_e32 v11, v61
	v_mov_b32_e32 v15, v176
	v_cvt_pk_bf16_f32 v92, v8, v9
	v_cvt_pk_bf16_f32 v93, v10, v11
	v_cvt_pk_bf16_f32 v94, v12, v13
	v_cvt_pk_bf16_f32 v95, v14, v15
	v_mul_f32_e32 v32, v32, v59
	v_mul_f32_e32 v36, v36, v59
	v_mul_f32_e32 v32, v32, v68
	v_mul_f32_e32 v36, v36, v72
	v_mul_f32_e32 v61, v36, v85
	v_mul_f32_e32 v176, v36, v84
	v_fma_f32 v61, v32, v84, -v61
	v_fma_f32 v176, v32, v85, v176
	v_mov_b32_e32 v32, v61
	v_mov_b32_e32 v36, v176
	v_mul_f32_e32 v33, v33, v59
	v_mul_f32_e32 v37, v37, v59
	v_mul_f32_e32 v33, v33, v69
	v_mul_f32_e32 v37, v37, v73
	v_mul_f32_e32 v61, v37, v87
	v_mul_f32_e32 v176, v37, v86
	v_fma_f32 v61, v33, v86, -v61
	v_fma_f32 v176, v33, v87, v176
	v_mov_b32_e32 v33, v61
	v_mov_b32_e32 v37, v176
	v_mul_f32_e32 v34, v34, v59
	v_mul_f32_e32 v38, v38, v59
	v_mul_f32_e32 v34, v34, v70
	v_mul_f32_e32 v38, v38, v74
	v_mul_f32_e32 v61, v38, v89
	v_mul_f32_e32 v176, v38, v88
	v_fma_f32 v61, v34, v88, -v61
	v_fma_f32 v176, v34, v89, v176
	v_mov_b32_e32 v34, v61
	v_mov_b32_e32 v38, v176
	v_mul_f32_e32 v35, v35, v59
	v_mul_f32_e32 v39, v39, v59
	v_mul_f32_e32 v35, v35, v71
	v_mul_f32_e32 v39, v39, v75
	v_mul_f32_e32 v61, v39, v91
	v_mul_f32_e32 v176, v39, v90
	v_fma_f32 v61, v35, v90, -v61
	v_fma_f32 v176, v35, v91, v176
	v_mov_b32_e32 v35, v61
	v_mov_b32_e32 v39, v176
	v_cvt_pk_bf16_f32 v96, v32, v33
	v_cvt_pk_bf16_f32 v97, v34, v35
	v_cvt_pk_bf16_f32 v98, v36, v37
	v_cvt_pk_bf16_f32 v99, v38, v39
	v_mul_f32_e32 v40, v40, v60
	v_mul_f32_e32 v44, v44, v60
	v_mul_f32_e32 v40, v40, v76
	v_mul_f32_e32 v44, v44, v80
	v_mul_f32_e32 v61, v44, v85
	v_mul_f32_e32 v176, v44, v84
	v_fma_f32 v61, v40, v84, -v61
	v_fma_f32 v176, v40, v85, v176
	v_mov_b32_e32 v40, v61
	v_mov_b32_e32 v44, v176
	v_mul_f32_e32 v41, v41, v60
	v_mul_f32_e32 v45, v45, v60
	v_mul_f32_e32 v41, v41, v77
	v_mul_f32_e32 v45, v45, v81
	v_mul_f32_e32 v61, v45, v87
	v_mul_f32_e32 v176, v45, v86
	v_fma_f32 v61, v41, v86, -v61
	v_fma_f32 v176, v41, v87, v176
	v_mov_b32_e32 v41, v61
	v_mov_b32_e32 v45, v176
	v_mul_f32_e32 v42, v42, v60
	v_mul_f32_e32 v46, v46, v60
	v_mul_f32_e32 v42, v42, v78
	v_mul_f32_e32 v46, v46, v82
	v_mul_f32_e32 v61, v46, v89
	v_mul_f32_e32 v176, v46, v88
	v_fma_f32 v61, v42, v88, -v61
	v_fma_f32 v176, v42, v89, v176
	v_mov_b32_e32 v42, v61
	v_mov_b32_e32 v46, v176
	v_mul_f32_e32 v43, v43, v60
	v_mul_f32_e32 v47, v47, v60
	v_mul_f32_e32 v43, v43, v79
	v_mul_f32_e32 v47, v47, v83
	v_mul_f32_e32 v61, v47, v91
	v_mul_f32_e32 v176, v47, v90
	v_fma_f32 v61, v43, v90, -v61
	v_fma_f32 v176, v43, v91, v176
	v_mov_b32_e32 v43, v61
	v_mov_b32_e32 v47, v176
	v_cvt_pk_bf16_f32 v100, v40, v41
	v_cvt_pk_bf16_f32 v101, v42, v43
	v_cvt_pk_bf16_f32 v102, v44, v45
	v_cvt_pk_bf16_f32 v103, v46, v47
	global_store_dwordx2 v[62:63], v[92:93], off
	global_store_dwordx2 v[62:63], v[94:95], off offset:64
	global_store_dwordx2 v[62:63], v[96:97], off offset:1024
	global_store_dwordx2 v[62:63], v[98:99], off offset:1088
	s_mov_b64 s[20:21], exec
	s_and_b64 exec, exec, s[10:11]
	global_store_dwordx2 v[64:65], v[100:101], off
	global_store_dwordx2 v[64:65], v[102:103], off offset:64
	s_mov_b64 exec, s[20:21]
	s_mov_b32 s25, s24
	s_cmp_lt_i32 s24, 0x8000
	s_cbranch_scc1 .Lfr_top
	s_branch .LBB0_1091
